# gather unit: page-table row preloaded per wave (bpermute lookup) and score loads hoisted above the new-key score computation
# speedup vs baseline: 1.0186x; 1.0018x over previous
.LBB0_2332:
	s_bfe_u32 s23, s54, 0x50003
	v_mbcnt_lo_u32_b32 v241, -1, 0
	v_mbcnt_hi_u32_b32 v241, -1, v241
	v_lshlrev_b32_e32 v241, 2, v241
	v_lshl_or_b32 v241, s23, 8, v241
	global_load_dword v240, v241, s[28:29]
	s_lshl_b32 s59, s23, 3
	s_and_b32 s22, s54, 7
	s_or_b32 s20, s59, 0x4000
	v_readfirstlane_b32 s55, v149
	s_or_b32 s58, s20, s22
	s_add_i32 s20, s55, s20
	s_ashr_i32 s21, s20, 31
	s_lshl_b32 s30, s58, 11
	s_lshl_b64 s[20:21], s[20:21], 7
	v_lshl_add_u64 v[4:5], v[140:141], 0, s[30:31]
	v_lshl_add_u64 v[12:13], v[142:143], 0, s[20:21]
	global_load_dwordx4 v[0:3], v[4:5], off
	s_nop 0
	global_load_dwordx4 v[4:7], v[4:5], off offset:16
	s_nop 0
	global_load_dwordx4 v[8:11], v[12:13], off
	s_nop 0
	global_load_dwordx4 v[12:15], v[12:13], off offset:16
	s_lshl_b32 s30, s58, 6
	v_lshl_add_u64 v[16:17], v[144:145], 0, s[30:31]
	global_load_dword v16, v[16:17], off
	s_and_b32 s20, s54, 0xff
	s_mul_i32 s30, s20, 0x8100
	v_lshl_add_u64 v[244:245], v[146:147], 0, s[30:31]
	global_load_dword v222, v[244:245], off
	global_load_dword v223, v[244:245], off offset:2048
	v_add_co_u32_e32 v246, vcc, 0x1000, v244
	s_nop 1
	v_addc_co_u32_e32 v247, vcc, 0, v245, vcc
	global_load_dword v224, v[246:247], off
	global_load_dword v225, v[246:247], off offset:2048
	v_add_co_u32_e32 v246, vcc, 0x2000, v244
	s_nop 1
	v_addc_co_u32_e32 v247, vcc, 0, v245, vcc
	global_load_dword v226, v[246:247], off
	global_load_dword v227, v[246:247], off offset:2048
	v_add_co_u32_e32 v246, vcc, 0x3000, v244
	s_nop 1
	v_addc_co_u32_e32 v247, vcc, 0, v245, vcc
	global_load_dword v228, v[246:247], off
	global_load_dword v229, v[246:247], off offset:2048
	v_add_co_u32_e32 v246, vcc, 0x4000, v244
	s_nop 1
	v_addc_co_u32_e32 v247, vcc, 0, v245, vcc
	global_load_dword v230, v[246:247], off
	global_load_dword v231, v[246:247], off offset:2048
	v_add_co_u32_e32 v246, vcc, 0x5000, v244
	s_nop 1
	v_addc_co_u32_e32 v247, vcc, 0, v245, vcc
	global_load_dword v232, v[246:247], off
	global_load_dword v233, v[246:247], off offset:2048
	v_add_co_u32_e32 v246, vcc, 0x6000, v244
	s_nop 1
	v_addc_co_u32_e32 v247, vcc, 0, v245, vcc
	global_load_dword v234, v[246:247], off
	global_load_dword v235, v[246:247], off offset:2048
	v_add_co_u32_e32 v246, vcc, 0x7000, v244
	s_nop 1
	v_addc_co_u32_e32 v247, vcc, 0, v245, vcc
	global_load_dword v236, v[246:247], off
	global_load_dword v237, v[246:247], off offset:2048
	s_waitcnt vmcnt(20)
	v_lshlrev_b32_e32 v17, 16, v0
	s_waitcnt vmcnt(18)
	v_lshlrev_b32_e32 v25, 16, v8
	v_and_b32_e32 v0, 0xffff0000, v0
	v_and_b32_e32 v8, 0xffff0000, v8
	v_fma_f32 v17, v17, v25, 0
	v_lshlrev_b32_e32 v18, 16, v1
	v_lshlrev_b32_e32 v26, 16, v9
	v_fmac_f32_e32 v17, v0, v8
	v_and_b32_e32 v1, 0xffff0000, v1
	v_and_b32_e32 v9, 0xffff0000, v9
	v_fmac_f32_e32 v17, v18, v26
	v_lshlrev_b32_e32 v19, 16, v2
	v_lshlrev_b32_e32 v27, 16, v10
	v_fmac_f32_e32 v17, v1, v9
	v_and_b32_e32 v2, 0xffff0000, v2
	v_and_b32_e32 v10, 0xffff0000, v10
	v_fmac_f32_e32 v17, v19, v27
	v_lshlrev_b32_e32 v20, 16, v3
	v_lshlrev_b32_e32 v28, 16, v11
	v_fmac_f32_e32 v17, v2, v10
	v_and_b32_e32 v3, 0xffff0000, v3
	v_and_b32_e32 v11, 0xffff0000, v11
	v_fmac_f32_e32 v17, v20, v28
	v_lshlrev_b32_e32 v21, 16, v4
	s_waitcnt vmcnt(17)
	v_lshlrev_b32_e32 v29, 16, v12
	v_fmac_f32_e32 v17, v3, v11
	v_and_b32_e32 v4, 0xffff0000, v4
	v_and_b32_e32 v12, 0xffff0000, v12
	v_fmac_f32_e32 v17, v21, v29
	v_lshlrev_b32_e32 v22, 16, v5
	v_lshlrev_b32_e32 v30, 16, v13
	v_fmac_f32_e32 v17, v4, v12
	v_and_b32_e32 v5, 0xffff0000, v5
	v_and_b32_e32 v13, 0xffff0000, v13
	v_fmac_f32_e32 v17, v22, v30
	v_lshlrev_b32_e32 v23, 16, v6
	v_lshlrev_b32_e32 v31, 16, v14
	v_fmac_f32_e32 v17, v5, v13
	v_and_b32_e32 v6, 0xffff0000, v6
	v_and_b32_e32 v14, 0xffff0000, v14
	v_fmac_f32_e32 v17, v23, v31
	v_lshlrev_b32_e32 v24, 16, v7
	v_lshlrev_b32_e32 v32, 16, v15
	v_fmac_f32_e32 v17, v6, v14
	v_and_b32_e32 v7, 0xffff0000, v7
	v_fmac_f32_e32 v17, v24, v32
	v_and_b32_e32 v0, 0xffff0000, v15
	v_fmac_f32_e32 v17, v7, v0
	ds_bpermute_b32 v0, v182, v17
	s_waitcnt lgkmcnt(0)
	v_add_f32_e32 v0, v17, v0
	ds_bpermute_b32 v1, v183, v0
	s_waitcnt lgkmcnt(0)
	v_add_f32_e32 v0, v0, v1
	v_max_f32_e32 v0, 0, v0
	s_waitcnt vmcnt(16)
	v_mul_f32_e32 v1, v16, v0
	ds_bpermute_b32 v1, v184, v1
	s_waitcnt lgkmcnt(0)
	v_fmac_f32_e32 v1, v16, v0
	ds_bpermute_b32 v0, v185, v1
	s_waitcnt lgkmcnt(0)
	v_add_f32_e32 v0, v1, v0
	ds_bpermute_b32 v1, v186, v0
	s_waitcnt lgkmcnt(0)
	v_add_f32_e32 v0, v0, v1
	ds_bpermute_b32 v1, v187, v0
	s_and_saveexec_b64 s[20:21], s[0:1]
	s_cbranch_execz .LBB0_2334
	s_cmp_le_i32 s55, s22
	s_cselect_b64 vcc, -1, 0
	s_lshl_b32 s30, s55, 2
	s_waitcnt lgkmcnt(0)
	v_add_f32_e32 v0, v0, v1
	s_add_i32 s30, s30, 0
	v_cndmask_b32_e32 v0, v217, v0, vcc
	v_mov_b32_e32 v1, s30
	ds_write_b32 v1, v0 offset:256
.LBB0_2334:
	s_or_b64 exec, exec, s[20:21]
	s_waitcnt vmcnt(0) lgkmcnt(0)
	v_mov_b32_e32 v19, v222
	v_mov_b32_e32 v18, v223
	v_mov_b32_e32 v17, v224
	v_mov_b32_e32 v16, v225
	v_mov_b32_e32 v15, v226
	v_mov_b32_e32 v14, v227
	v_mov_b32_e32 v13, v228
	v_mov_b32_e32 v12, v229
	v_mov_b32_e32 v11, v230
	v_mov_b32_e32 v10, v231
	v_mov_b32_e32 v9, v232
	v_mov_b32_e32 v8, v233
	v_mov_b32_e32 v7, v234
	v_mov_b32_e32 v6, v235
	v_mov_b32_e32 v5, v236
	v_mov_b32_e32 v4, v237
	v_mov_b32_e32 v20, 0xff800000
	s_barrier
	s_and_saveexec_b64 s[20:21], s[2:3]
	ds_read_b32 v20, v188 offset:256
	s_or_b64 exec, exec, s[20:21]
	s_waitcnt vmcnt(15)
	v_cmp_lt_f32_e32 vcc, s45, v19
	s_nop 1
	v_cndmask_b32_e32 v1, 0, v19, vcc
	s_waitcnt vmcnt(14)
	v_cmp_lt_f32_e32 vcc, s45, v18
	v_add_f32_e32 v0, 0, v1
	v_mul_f32_e32 v3, v1, v1
	v_cndmask_b32_e32 v2, 0, v18, vcc
	s_waitcnt vmcnt(13)
	v_cmp_lt_f32_e32 vcc, s45, v17
	v_mul_f32_e32 v1, v2, v2
	v_pk_add_f32 v[0:1], v[0:1], v[2:3]
	v_cndmask_b32_e32 v22, 0, v17, vcc
	s_waitcnt vmcnt(12)
	v_cmp_lt_f32_e32 vcc, s45, v16
	v_mul_f32_e32 v23, v22, v22
	v_pk_add_f32 v[0:1], v[0:1], v[22:23]
	v_cndmask_b32_e32 v24, 0, v16, vcc
	s_waitcnt vmcnt(11)
	v_cmp_lt_f32_e32 vcc, s45, v15
	v_mul_f32_e32 v25, v24, v24
	v_pk_add_f32 v[0:1], v[0:1], v[24:25]
	v_cndmask_b32_e32 v26, 0, v15, vcc
	s_waitcnt vmcnt(10)
	v_cmp_lt_f32_e32 vcc, s45, v14
	v_mul_f32_e32 v27, v26, v26
	v_pk_add_f32 v[0:1], v[0:1], v[26:27]
	v_cndmask_b32_e32 v28, 0, v14, vcc
	s_waitcnt vmcnt(9)
	v_cmp_lt_f32_e32 vcc, s45, v13
	v_mul_f32_e32 v29, v28, v28
	v_pk_add_f32 v[0:1], v[0:1], v[28:29]
	v_cndmask_b32_e32 v30, 0, v13, vcc
	s_waitcnt vmcnt(8)
	v_cmp_lt_f32_e32 vcc, s45, v12
	v_mul_f32_e32 v31, v30, v30
	v_pk_add_f32 v[0:1], v[0:1], v[30:31]
	v_cndmask_b32_e32 v32, 0, v12, vcc
	s_waitcnt vmcnt(7)
	v_cmp_lt_f32_e32 vcc, s45, v11
	v_mul_f32_e32 v33, v32, v32
	v_pk_add_f32 v[0:1], v[0:1], v[32:33]
	v_cndmask_b32_e32 v34, 0, v11, vcc
	s_waitcnt vmcnt(6)
	v_cmp_lt_f32_e32 vcc, s45, v10
	v_mul_f32_e32 v35, v34, v34
	v_pk_add_f32 v[0:1], v[0:1], v[34:35]
	v_cndmask_b32_e32 v36, 0, v10, vcc
	s_waitcnt vmcnt(5)
	v_cmp_lt_f32_e32 vcc, s45, v9
	v_mul_f32_e32 v37, v36, v36
	v_pk_add_f32 v[0:1], v[0:1], v[36:37]
	v_cndmask_b32_e32 v38, 0, v9, vcc
	s_waitcnt vmcnt(4)
	v_cmp_lt_f32_e32 vcc, s45, v8
	v_mul_f32_e32 v39, v38, v38
	v_pk_add_f32 v[0:1], v[0:1], v[38:39]
	v_cndmask_b32_e32 v40, 0, v8, vcc
	s_waitcnt vmcnt(3)
	v_cmp_lt_f32_e32 vcc, s45, v7
	v_mul_f32_e32 v41, v40, v40
	v_pk_add_f32 v[0:1], v[0:1], v[40:41]
	v_cndmask_b32_e32 v2, 0, v7, vcc
	s_waitcnt vmcnt(2)
	v_cmp_lt_f32_e32 vcc, s45, v6
	v_mul_f32_e32 v3, v2, v2
	v_pk_add_f32 v[0:1], v[0:1], v[2:3]
	v_cndmask_b32_e32 v22, 0, v6, vcc
	s_waitcnt vmcnt(1)
	v_cmp_lt_f32_e32 vcc, s45, v5
	v_mul_f32_e32 v23, v22, v22
	v_pk_add_f32 v[0:1], v[0:1], v[22:23]
	v_cndmask_b32_e32 v24, 0, v5, vcc
	s_waitcnt vmcnt(0)
	v_cmp_lt_f32_e32 vcc, s45, v4
	v_mul_f32_e32 v25, v24, v24
	v_pk_add_f32 v[0:1], v[0:1], v[24:25]
	v_cndmask_b32_e32 v26, 0, v4, vcc
	s_waitcnt lgkmcnt(0)
	v_cmp_lt_f32_e32 vcc, s45, v20
	v_mul_f32_e32 v27, v26, v26
	v_pk_add_f32 v[0:1], v[0:1], v[26:27]
	v_cndmask_b32_e32 v28, 0, v20, vcc
	v_mul_f32_e32 v29, v28, v28
	v_pk_add_f32 v[0:1], v[0:1], v[28:29]
	ds_bpermute_b32 v2, v182, v0
	ds_bpermute_b32 v3, v182, v1
	s_waitcnt lgkmcnt(0)
	v_pk_add_f32 v[0:1], v[0:1], v[2:3]
	ds_bpermute_b32 v2, v183, v0
	ds_bpermute_b32 v3, v183, v1
	s_waitcnt lgkmcnt(0)
	v_pk_add_f32 v[0:1], v[0:1], v[2:3]
	ds_bpermute_b32 v2, v184, v0
	ds_bpermute_b32 v3, v184, v1
	s_waitcnt lgkmcnt(0)
	v_pk_add_f32 v[0:1], v[0:1], v[2:3]
	ds_bpermute_b32 v2, v185, v0
	ds_bpermute_b32 v3, v185, v1
	s_waitcnt lgkmcnt(0)
	v_pk_add_f32 v[0:1], v[0:1], v[2:3]
	ds_bpermute_b32 v2, v186, v0
	ds_bpermute_b32 v3, v186, v1
	s_waitcnt lgkmcnt(0)
	v_pk_add_f32 v[0:1], v[0:1], v[2:3]
	ds_bpermute_b32 v2, v187, v0
	ds_bpermute_b32 v3, v187, v1
	s_and_saveexec_b64 s[20:21], s[0:1]
	s_cbranch_execz .LBB0_2338
	s_lshl_b32 s30, s55, 3
	s_add_i32 s30, s30, 0
	s_waitcnt lgkmcnt(0)
	v_pk_add_f32 v[0:1], v[0:1], v[2:3]
	v_mov_b32_e32 v2, s30
	ds_write_b64 v2, v[0:1]

.LBB0_2437:
	s_or_b64 exec, exec, s[38:39]
	v_cmp_gt_i32_e64 s[20:21], s33, v1
	s_and_b64 s[38:39], vcc, s[20:21]
	s_and_saveexec_b64 s[20:21], s[38:39]
	v_lshl_add_u32 v0, v1, 2, 0
	ds_write_b32 v0, v210 offset:512
	s_or_b64 exec, exec, s[20:21]
	s_waitcnt lgkmcnt(0)
	s_barrier
	s_and_saveexec_b64 s[20:21], s[16:17]
	s_cbranch_execz .LBB0_2447
	ds_read_b32 v4, v188 offset:512
	v_mov_b64_e32 v[0:1], 0
	v_mov_b64_e32 v[2:3], 0
	s_waitcnt vmcnt(0) lgkmcnt(0)
	v_lshrrev_b32_e32 v242, 5, v4
	v_and_b32_e32 v242, 0xfc, v242
	ds_bpermute_b32 v242, v242, v240
	v_cmp_lt_i32_e32 vcc, -1, v4
	s_and_saveexec_b64 s[38:39], vcc
	s_cbranch_execz .LBB0_2446
	v_cmp_lt_u32_e32 vcc, s51, v4
	s_and_saveexec_b64 s[40:41], vcc
	s_xor_b64 s[40:41], exec, s[40:41]
	v_add_u32_e32 v0, s59, v4
	v_add_u32_e32 v0, 0xffffe000, v0
	v_mov_b32_e32 v1, v138
	v_lshlrev_b64 v[2:3], 11, v[0:1]
	v_lshl_add_u64 v[0:1], s[34:35], 0, v[2:3]
	v_lshl_add_u64 v[2:3], s[36:37], 0, v[2:3]
	s_andn2_saveexec_b64 s[40:41], s[40:41]
	s_cbranch_execz .LBB0_2445
	v_lshlrev_b32_e32 v4, 11, v4
	s_waitcnt lgkmcnt(0)
	v_mov_b32_e32 v0, v242
	v_ashrrev_i32_e32 v1, 31, v0
	v_lshlrev_b64 v[2:3], 18, v[0:1]
	v_and_or_b32 v2, v4, s52, v2
	v_lshl_add_u64 v[0:1], s[24:25], 0, v[2:3]
	v_lshl_add_u64 v[2:3], s[26:27], 0, v[2:3]

.LBB0_2703:
	s_bfe_u32 s23, s58, 0x50003
	v_mbcnt_lo_u32_b32 v241, -1, 0
	v_mbcnt_hi_u32_b32 v241, -1, v241
	v_lshlrev_b32_e32 v241, 2, v241
	v_lshl_or_b32 v241, s23, 8, v241
	global_load_dword v240, v241, s[28:29]
	s_lshl_b32 s61, s23, 3
	s_and_b32 s22, s58, 7
	s_or_b32 s20, s61, 0x4000
	v_readfirstlane_b32 s59, v149
	s_or_b32 s60, s20, s22
	s_add_i32 s20, s59, s20
	s_ashr_i32 s21, s20, 31
	s_lshl_b32 s30, s60, 11
	s_lshl_b64 s[20:21], s[20:21], 7
	v_lshl_add_u64 v[4:5], v[140:141], 0, s[30:31]
	v_lshl_add_u64 v[12:13], v[142:143], 0, s[20:21]
	global_load_dwordx4 v[0:3], v[4:5], off
	s_nop 0
	global_load_dwordx4 v[4:7], v[4:5], off offset:16
	s_nop 0
	global_load_dwordx4 v[8:11], v[12:13], off
	s_nop 0
	global_load_dwordx4 v[12:15], v[12:13], off offset:16
	s_lshl_b32 s30, s60, 6
	v_lshl_add_u64 v[16:17], v[144:145], 0, s[30:31]
	global_load_dword v16, v[16:17], off
	s_and_b32 s20, s58, 0xff
	s_mul_i32 s30, s20, 0x8100
	v_lshl_add_u64 v[244:245], v[146:147], 0, s[30:31]
	global_load_dword v222, v[244:245], off
	global_load_dword v223, v[244:245], off offset:2048
	v_add_co_u32_e32 v246, vcc, 0x1000, v244
	s_nop 1
	v_addc_co_u32_e32 v247, vcc, 0, v245, vcc
	global_load_dword v224, v[246:247], off
	global_load_dword v225, v[246:247], off offset:2048
	v_add_co_u32_e32 v246, vcc, 0x2000, v244
	s_nop 1
	v_addc_co_u32_e32 v247, vcc, 0, v245, vcc
	global_load_dword v226, v[246:247], off
	global_load_dword v227, v[246:247], off offset:2048
	v_add_co_u32_e32 v246, vcc, 0x3000, v244
	s_nop 1
	v_addc_co_u32_e32 v247, vcc, 0, v245, vcc
	global_load_dword v228, v[246:247], off
	global_load_dword v229, v[246:247], off offset:2048
	v_add_co_u32_e32 v246, vcc, 0x4000, v244
	s_nop 1
	v_addc_co_u32_e32 v247, vcc, 0, v245, vcc
	global_load_dword v230, v[246:247], off
	global_load_dword v231, v[246:247], off offset:2048
	v_add_co_u32_e32 v246, vcc, 0x5000, v244
	s_nop 1
	v_addc_co_u32_e32 v247, vcc, 0, v245, vcc
	global_load_dword v232, v[246:247], off
	global_load_dword v233, v[246:247], off offset:2048
	v_add_co_u32_e32 v246, vcc, 0x6000, v244
	s_nop 1
	v_addc_co_u32_e32 v247, vcc, 0, v245, vcc
	global_load_dword v234, v[246:247], off
	global_load_dword v235, v[246:247], off offset:2048
	v_add_co_u32_e32 v246, vcc, 0x7000, v244
	s_nop 1
	v_addc_co_u32_e32 v247, vcc, 0, v245, vcc
	global_load_dword v236, v[246:247], off
	global_load_dword v237, v[246:247], off offset:2048
	s_waitcnt vmcnt(20)
	v_lshlrev_b32_e32 v17, 16, v0
	s_waitcnt vmcnt(18)
	v_lshlrev_b32_e32 v25, 16, v8
	v_and_b32_e32 v0, 0xffff0000, v0
	v_and_b32_e32 v8, 0xffff0000, v8
	v_fma_f32 v17, v17, v25, 0
	v_lshlrev_b32_e32 v18, 16, v1
	v_lshlrev_b32_e32 v26, 16, v9
	v_fmac_f32_e32 v17, v0, v8
	v_and_b32_e32 v1, 0xffff0000, v1
	v_and_b32_e32 v9, 0xffff0000, v9
	v_fmac_f32_e32 v17, v18, v26
	v_lshlrev_b32_e32 v19, 16, v2
	v_lshlrev_b32_e32 v27, 16, v10
	v_fmac_f32_e32 v17, v1, v9
	v_and_b32_e32 v2, 0xffff0000, v2
	v_and_b32_e32 v10, 0xffff0000, v10
	v_fmac_f32_e32 v17, v19, v27
	v_lshlrev_b32_e32 v20, 16, v3
	v_lshlrev_b32_e32 v28, 16, v11
	v_fmac_f32_e32 v17, v2, v10
	v_and_b32_e32 v3, 0xffff0000, v3
	v_and_b32_e32 v11, 0xffff0000, v11
	v_fmac_f32_e32 v17, v20, v28
	v_lshlrev_b32_e32 v21, 16, v4
	s_waitcnt vmcnt(17)
	v_lshlrev_b32_e32 v29, 16, v12
	v_fmac_f32_e32 v17, v3, v11
	v_and_b32_e32 v4, 0xffff0000, v4
	v_and_b32_e32 v12, 0xffff0000, v12
	v_fmac_f32_e32 v17, v21, v29
	v_lshlrev_b32_e32 v22, 16, v5
	v_lshlrev_b32_e32 v30, 16, v13
	v_fmac_f32_e32 v17, v4, v12
	v_and_b32_e32 v5, 0xffff0000, v5
	v_and_b32_e32 v13, 0xffff0000, v13
	v_fmac_f32_e32 v17, v22, v30
	v_lshlrev_b32_e32 v23, 16, v6
	v_lshlrev_b32_e32 v31, 16, v14
	v_fmac_f32_e32 v17, v5, v13
	v_and_b32_e32 v6, 0xffff0000, v6
	v_and_b32_e32 v14, 0xffff0000, v14
	v_fmac_f32_e32 v17, v23, v31
	v_lshlrev_b32_e32 v24, 16, v7
	v_lshlrev_b32_e32 v32, 16, v15
	v_fmac_f32_e32 v17, v6, v14
	v_and_b32_e32 v7, 0xffff0000, v7
	v_fmac_f32_e32 v17, v24, v32
	v_and_b32_e32 v0, 0xffff0000, v15
	v_fmac_f32_e32 v17, v7, v0
	ds_bpermute_b32 v0, v182, v17
	s_waitcnt lgkmcnt(0)
	v_add_f32_e32 v0, v17, v0
	ds_bpermute_b32 v1, v183, v0
	s_waitcnt lgkmcnt(0)
	v_add_f32_e32 v0, v0, v1
	v_max_f32_e32 v0, 0, v0
	s_waitcnt vmcnt(16)
	v_mul_f32_e32 v1, v16, v0
	ds_bpermute_b32 v1, v184, v1
	s_waitcnt lgkmcnt(0)
	v_fmac_f32_e32 v1, v16, v0
	ds_bpermute_b32 v0, v185, v1
	s_waitcnt lgkmcnt(0)
	v_add_f32_e32 v0, v1, v0
	ds_bpermute_b32 v1, v186, v0
	s_waitcnt lgkmcnt(0)
	v_add_f32_e32 v0, v0, v1
	ds_bpermute_b32 v1, v187, v0
	s_and_saveexec_b64 s[20:21], s[0:1]
	s_cbranch_execz .LBB0_2705
	s_cmp_le_i32 s59, s22
	s_cselect_b64 vcc, -1, 0
	s_lshl_b32 s30, s59, 2
	s_waitcnt lgkmcnt(0)
	v_add_f32_e32 v0, v0, v1
	s_add_i32 s30, s30, 0
	v_cndmask_b32_e32 v0, v217, v0, vcc
	v_mov_b32_e32 v1, s30
	ds_write_b32 v1, v0 offset:256
.LBB0_2705:
	s_or_b64 exec, exec, s[20:21]
	s_waitcnt vmcnt(0) lgkmcnt(0)
	v_mov_b32_e32 v19, v222
	v_mov_b32_e32 v18, v223
	v_mov_b32_e32 v17, v224
	v_mov_b32_e32 v16, v225
	v_mov_b32_e32 v15, v226
	v_mov_b32_e32 v14, v227
	v_mov_b32_e32 v13, v228
	v_mov_b32_e32 v12, v229
	v_mov_b32_e32 v11, v230
	v_mov_b32_e32 v10, v231
	v_mov_b32_e32 v9, v232
	v_mov_b32_e32 v8, v233
	v_mov_b32_e32 v7, v234
	v_mov_b32_e32 v6, v235
	v_mov_b32_e32 v5, v236
	v_mov_b32_e32 v4, v237
	v_mov_b32_e32 v20, 0xff800000
	s_barrier
	s_and_saveexec_b64 s[20:21], s[2:3]
	ds_read_b32 v20, v188 offset:256
	s_or_b64 exec, exec, s[20:21]
	s_waitcnt vmcnt(15)
	v_cmp_lt_f32_e32 vcc, s47, v19
	s_nop 1
	v_cndmask_b32_e32 v1, 0, v19, vcc
	s_waitcnt vmcnt(14)
	v_cmp_lt_f32_e32 vcc, s47, v18
	v_add_f32_e32 v0, 0, v1
	v_mul_f32_e32 v3, v1, v1
	v_cndmask_b32_e32 v2, 0, v18, vcc
	s_waitcnt vmcnt(13)
	v_cmp_lt_f32_e32 vcc, s47, v17
	v_mul_f32_e32 v1, v2, v2
	v_pk_add_f32 v[0:1], v[0:1], v[2:3]
	v_cndmask_b32_e32 v22, 0, v17, vcc
	s_waitcnt vmcnt(12)
	v_cmp_lt_f32_e32 vcc, s47, v16
	v_mul_f32_e32 v23, v22, v22
	v_pk_add_f32 v[0:1], v[0:1], v[22:23]
	v_cndmask_b32_e32 v24, 0, v16, vcc
	s_waitcnt vmcnt(11)
	v_cmp_lt_f32_e32 vcc, s47, v15
	v_mul_f32_e32 v25, v24, v24
	v_pk_add_f32 v[0:1], v[0:1], v[24:25]
	v_cndmask_b32_e32 v26, 0, v15, vcc
	s_waitcnt vmcnt(10)
	v_cmp_lt_f32_e32 vcc, s47, v14
	v_mul_f32_e32 v27, v26, v26
	v_pk_add_f32 v[0:1], v[0:1], v[26:27]
	v_cndmask_b32_e32 v28, 0, v14, vcc
	s_waitcnt vmcnt(9)
	v_cmp_lt_f32_e32 vcc, s47, v13
	v_mul_f32_e32 v29, v28, v28
	v_pk_add_f32 v[0:1], v[0:1], v[28:29]
	v_cndmask_b32_e32 v30, 0, v13, vcc
	s_waitcnt vmcnt(8)
	v_cmp_lt_f32_e32 vcc, s47, v12
	v_mul_f32_e32 v31, v30, v30
	v_pk_add_f32 v[0:1], v[0:1], v[30:31]
	v_cndmask_b32_e32 v32, 0, v12, vcc
	s_waitcnt vmcnt(7)
	v_cmp_lt_f32_e32 vcc, s47, v11
	v_mul_f32_e32 v33, v32, v32
	v_pk_add_f32 v[0:1], v[0:1], v[32:33]
	v_cndmask_b32_e32 v34, 0, v11, vcc
	s_waitcnt vmcnt(6)
	v_cmp_lt_f32_e32 vcc, s47, v10
	v_mul_f32_e32 v35, v34, v34
	v_pk_add_f32 v[0:1], v[0:1], v[34:35]
	v_cndmask_b32_e32 v36, 0, v10, vcc
	s_waitcnt vmcnt(5)
	v_cmp_lt_f32_e32 vcc, s47, v9
	v_mul_f32_e32 v37, v36, v36
	v_pk_add_f32 v[0:1], v[0:1], v[36:37]
	v_cndmask_b32_e32 v38, 0, v9, vcc
	s_waitcnt vmcnt(4)
	v_cmp_lt_f32_e32 vcc, s47, v8
	v_mul_f32_e32 v39, v38, v38
	v_pk_add_f32 v[0:1], v[0:1], v[38:39]
	v_cndmask_b32_e32 v40, 0, v8, vcc
	s_waitcnt vmcnt(3)
	v_cmp_lt_f32_e32 vcc, s47, v7
	v_mul_f32_e32 v41, v40, v40
	v_pk_add_f32 v[0:1], v[0:1], v[40:41]
	v_cndmask_b32_e32 v2, 0, v7, vcc
	s_waitcnt vmcnt(2)
	v_cmp_lt_f32_e32 vcc, s47, v6
	v_mul_f32_e32 v3, v2, v2
	v_pk_add_f32 v[0:1], v[0:1], v[2:3]
	v_cndmask_b32_e32 v22, 0, v6, vcc
	s_waitcnt vmcnt(1)
	v_cmp_lt_f32_e32 vcc, s47, v5
	v_mul_f32_e32 v23, v22, v22
	v_pk_add_f32 v[0:1], v[0:1], v[22:23]
	v_cndmask_b32_e32 v24, 0, v5, vcc
	s_waitcnt vmcnt(0)
	v_cmp_lt_f32_e32 vcc, s47, v4
	v_mul_f32_e32 v25, v24, v24
	v_pk_add_f32 v[0:1], v[0:1], v[24:25]
	v_cndmask_b32_e32 v26, 0, v4, vcc
	s_waitcnt lgkmcnt(0)
	v_cmp_lt_f32_e32 vcc, s47, v20
	v_mul_f32_e32 v27, v26, v26
	v_pk_add_f32 v[0:1], v[0:1], v[26:27]
	v_cndmask_b32_e32 v28, 0, v20, vcc
	v_mul_f32_e32 v29, v28, v28
	v_pk_add_f32 v[0:1], v[0:1], v[28:29]
	ds_bpermute_b32 v2, v182, v0
	ds_bpermute_b32 v3, v182, v1
	s_waitcnt lgkmcnt(0)
	v_pk_add_f32 v[0:1], v[0:1], v[2:3]
	ds_bpermute_b32 v2, v183, v0
	ds_bpermute_b32 v3, v183, v1
	s_waitcnt lgkmcnt(0)
	v_pk_add_f32 v[0:1], v[0:1], v[2:3]
	ds_bpermute_b32 v2, v184, v0
	ds_bpermute_b32 v3, v184, v1
	s_waitcnt lgkmcnt(0)
	v_pk_add_f32 v[0:1], v[0:1], v[2:3]
	ds_bpermute_b32 v2, v185, v0
	ds_bpermute_b32 v3, v185, v1
	s_waitcnt lgkmcnt(0)
	v_pk_add_f32 v[0:1], v[0:1], v[2:3]
	ds_bpermute_b32 v2, v186, v0
	ds_bpermute_b32 v3, v186, v1
	s_waitcnt lgkmcnt(0)
	v_pk_add_f32 v[0:1], v[0:1], v[2:3]
	ds_bpermute_b32 v2, v187, v0
	ds_bpermute_b32 v3, v187, v1
	s_and_saveexec_b64 s[20:21], s[0:1]
	s_cbranch_execz .LBB0_2709
	s_lshl_b32 s30, s59, 3
	s_add_i32 s30, s30, 0
	s_waitcnt lgkmcnt(0)
	v_pk_add_f32 v[0:1], v[0:1], v[2:3]
	v_mov_b32_e32 v2, s30
	ds_write_b64 v2, v[0:1]

.LBB0_2808:
	s_or_b64 exec, exec, s[38:39]
	v_cmp_gt_i32_e64 s[20:21], s33, v1
	s_and_b64 s[38:39], vcc, s[20:21]
	s_and_saveexec_b64 s[20:21], s[38:39]
	v_lshl_add_u32 v0, v1, 2, 0
	ds_write_b32 v0, v210 offset:512
	s_or_b64 exec, exec, s[20:21]
	s_waitcnt lgkmcnt(0)
	s_barrier
	s_and_saveexec_b64 s[20:21], s[16:17]
	s_cbranch_execz .LBB0_2818
	ds_read_b32 v4, v188 offset:512
	v_mov_b64_e32 v[0:1], 0
	v_mov_b64_e32 v[2:3], 0
	s_waitcnt vmcnt(0) lgkmcnt(0)
	v_lshrrev_b32_e32 v242, 5, v4
	v_and_b32_e32 v242, 0xfc, v242
	ds_bpermute_b32 v242, v242, v240
	v_cmp_lt_i32_e32 vcc, -1, v4
	s_and_saveexec_b64 s[38:39], vcc
	s_cbranch_execz .LBB0_2817
	v_cmp_lt_u32_e32 vcc, s53, v4
	s_and_saveexec_b64 s[40:41], vcc
	s_xor_b64 s[40:41], exec, s[40:41]
	v_add_u32_e32 v0, s61, v4
	v_add_u32_e32 v0, 0xffffe000, v0
	v_mov_b32_e32 v1, v138
	v_lshlrev_b64 v[2:3], 11, v[0:1]
	v_lshl_add_u64 v[0:1], s[34:35], 0, v[2:3]
	v_lshl_add_u64 v[2:3], s[36:37], 0, v[2:3]
	s_andn2_saveexec_b64 s[40:41], s[40:41]
	s_cbranch_execz .LBB0_2816
	v_lshlrev_b32_e32 v4, 11, v4
	s_waitcnt lgkmcnt(0)
	v_mov_b32_e32 v0, v242
	v_ashrrev_i32_e32 v1, 31, v0
	v_lshlrev_b64 v[2:3], 18, v[0:1]
	v_and_or_b32 v2, v4, s54, v2
	v_lshl_add_u64 v[0:1], s[24:25], 0, v[2:3]
	v_lshl_add_u64 v[2:3], s[26:27], 0, v[2:3]
